# latent attention: next tile's fragment LDS addresses computed before the tile barrier, so the fragment reads issue right after it
# speedup vs baseline: 1.0018x; 1.0018x over previous
.LBB0_208:
	s_add_i32 s9, s64, 0x4000
	s_and_b32 s9, s9, 0x4000
	v_add_u32_e32 v222, s9, v177
	v_add_u32_e32 v197, v222, v176
	v_add_u32_e32 v202, v222, v175
	v_add_u32_e32 v203, v222, v173
	v_add_u32_e32 v204, v222, v171
	v_add_u32_e32 v205, s9, v174
	v_add_u32_e32 v206, v205, v176
	v_add_u32_e32 v207, v205, v175
	v_add_u32_e32 v208, v205, v173
	v_add_u32_e32 v205, v205, v171
	global_load_dwordx4 v[152:155], v167, s[48:49]
	global_load_dwordx4 v[156:159], v167, s[4:5]
	s_cmp_lt_u32 s41, 34
	s_cselect_b64 s[0:1], -1, 0
	s_cmp_gt_u32 s41, 33
	s_cbranch_scc1 .LBB0_210
	global_load_dwordx4 v[128:131], v178, s[2:3]
	global_load_dwordx4 v[132:135], v178, s[62:63]
.LBB0_210:
	s_add_i32 s71, s64, 0x4000
	ds_read_b128 v[214:217], v197 offset:4096
	ds_read_b128 v[218:221], v202 offset:4096
	ds_read_b128 v[246:249], v203 offset:4096
	ds_read_b128 v[236:239], v204 offset:4096
	ds_read_b128 v[198:201], v206 offset:32768
	v_exp_f32_e32 v179, v80
	v_exp_f32_e32 v180, v81
	v_exp_f32_e32 v181, v82
	v_exp_f32_e32 v182, v83
	v_exp_f32_e32 v183, v84
	v_exp_f32_e32 v184, v85
	v_exp_f32_e32 v185, v86
	v_exp_f32_e32 v186, v87
	v_exp_f32_e32 v187, v88
	v_exp_f32_e32 v188, v89
	v_exp_f32_e32 v189, v90
	v_exp_f32_e32 v190, v91
	v_exp_f32_e32 v191, v92
	v_exp_f32_e32 v194, v93
	v_exp_f32_e32 v195, v94
	v_exp_f32_e32 v196, v95
	s_and_b32 s9, s64, 0x4000
	s_add_i32 s46, s9, 0
	v_add_u32_e32 v213, s46, v165
	s_andn2_b64 vcc, exec, s[0:1]
	s_waitcnt lgkmcnt(4)
	v_mfma_f32_32x32x16_bf16 v[80:95], v[214:217], v[112:115], v[64:79]
	ds_read_b128 v[214:217], v206 offset:36864
	v_exp_f32_e32 v209, v108
	s_waitcnt lgkmcnt(4)
	v_mfma_f32_32x32x16_bf16 v[80:95], v[218:221], v[116:119], v[80:95]
	ds_read_b128 v[218:221], v206 offset:40960
	v_exp_f32_e32 v210, v109
	s_waitcnt lgkmcnt(4)
	v_mfma_f32_32x32x16_bf16 v[80:95], v[246:249], v[120:123], v[80:95]
	ds_read_b128 v[246:249], v206 offset:45056
	v_exp_f32_e32 v206, v105
	s_waitcnt lgkmcnt(4)
	v_mfma_f32_32x32x16_bf16 v[80:95], v[236:239], v[124:127], v[80:95]
	ds_read_b128 v[236:239], v207 offset:32768
	v_exp_f32_e32 v211, v110
	s_waitcnt lgkmcnt(4)
	v_mfma_f32_32x32x16_bf16 v[48:63], v[198:201], v[148:151], v[48:63]
	ds_read_b128 v[198:201], v207 offset:36864
	v_exp_f32_e32 v212, v111
	s_waitcnt lgkmcnt(4)
	v_mfma_f32_32x32x16_bf16 v[32:47], v[214:217], v[148:151], v[32:47]
	ds_read_b128 v[214:217], v207 offset:40960
	s_waitcnt lgkmcnt(4)
	v_mfma_f32_32x32x16_bf16 v[16:31], v[218:221], v[148:151], v[16:31]
	ds_read_b128 v[218:221], v207 offset:45056
	v_exp_f32_e32 v207, v106
	s_waitcnt lgkmcnt(4)
	v_mfma_f32_32x32x16_bf16 v[0:15], v[246:249], v[148:151], v[0:15]
	ds_read_b128 v[246:249], v208 offset:32768
	s_waitcnt lgkmcnt(4)
	v_mfma_f32_32x32x16_bf16 v[48:63], v[236:239], v[144:147], v[48:63]
	ds_read_b128 v[236:239], v208 offset:36864
	s_waitcnt lgkmcnt(4)
	v_mfma_f32_32x32x16_bf16 v[32:47], v[198:201], v[144:147], v[32:47]
	ds_read_b128 v[198:201], v208 offset:40960
	s_waitcnt lgkmcnt(4)
	v_mfma_f32_32x32x16_bf16 v[16:31], v[214:217], v[144:147], v[16:31]
	ds_read_b128 v[214:217], v208 offset:45056
	v_exp_f32_e32 v208, v107
	s_waitcnt lgkmcnt(4)
	v_mfma_f32_32x32x16_bf16 v[0:15], v[218:221], v[144:147], v[0:15]
	ds_read_b128 v[218:221], v205 offset:32768
	s_waitcnt lgkmcnt(4)
	v_mfma_f32_32x32x16_bf16 v[48:63], v[246:249], v[140:143], v[48:63]
	ds_read_b128 v[246:249], v205 offset:36864
	s_waitcnt lgkmcnt(4)
	v_mfma_f32_32x32x16_bf16 v[32:47], v[236:239], v[140:143], v[32:47]
	ds_read_b128 v[236:239], v205 offset:40960
	s_waitcnt lgkmcnt(4)
	v_mfma_f32_32x32x16_bf16 v[16:31], v[198:201], v[140:143], v[16:31]
	ds_read_b128 v[148:151], v205 offset:45056
	v_exp_f32_e32 v205, v104
	v_exp_f32_e32 v198, v97
	v_exp_f32_e32 v199, v98
	s_waitcnt lgkmcnt(4)
	v_mfma_f32_32x32x16_bf16 v[0:15], v[214:217], v[140:143], v[0:15]
	ds_read_b128 v[214:217], v197
	v_exp_f32_e32 v197, v96
	v_exp_f32_e32 v200, v99
	v_exp_f32_e32 v201, v100
	s_waitcnt lgkmcnt(4)
	v_mfma_f32_32x32x16_bf16 v[48:63], v[218:221], v[136:139], v[48:63]
	ds_read_b128 v[218:221], v202
	v_exp_f32_e32 v202, v101
	v_add_f32_e32 v222, v197, v179
	v_add_f32_e32 v223, 0, v222
	v_add_f32_e32 v222, v198, v180
	v_add_f32_e32 v223, v222, v223
	v_add_f32_e32 v222, v199, v181
	v_add_f32_e32 v223, v222, v223
	s_waitcnt lgkmcnt(4)
	v_mfma_f32_32x32x16_bf16 v[32:47], v[246:249], v[136:139], v[32:47]
	ds_read_b128 v[246:249], v203
	v_exp_f32_e32 v203, v102
	v_add_f32_e32 v222, v200, v182
	v_add_f32_e32 v223, v222, v223
	v_add_f32_e32 v222, v201, v183
	v_add_f32_e32 v223, v222, v223
	v_add_f32_e32 v222, v202, v184
	v_add_f32_e32 v223, v222, v223
	s_waitcnt lgkmcnt(4)
	v_mfma_f32_32x32x16_bf16 v[16:31], v[236:239], v[136:139], v[16:31]
	ds_read_b128 v[236:239], v204
	v_exp_f32_e32 v204, v103
	v_add_f32_e32 v222, v203, v185
	v_add_f32_e32 v223, v222, v223
	s_waitcnt lgkmcnt(4)
	v_mfma_f32_32x32x16_bf16 v[0:15], v[148:151], v[136:139], v[0:15]
	v_add_f32_e32 v222, v204, v186
	v_add_f32_e32 v223, v222, v223
	v_cvt_pk_bf16_f32 v148, v197, v198
	v_cvt_pk_bf16_f32 v149, v199, v200
	v_cvt_pk_bf16_f32 v150, v201, v202
	v_cvt_pk_bf16_f32 v151, v203, v204
	v_cvt_pk_bf16_f32 v140, v179, v180
	v_cvt_pk_bf16_f32 v141, v181, v182
	v_cvt_pk_bf16_f32 v142, v183, v184
	s_waitcnt lgkmcnt(3)
	v_mfma_f32_32x32x16_bf16 v[96:111], v[214:217], v[112:115], v[64:79]
	v_add_f32_e32 v222, v205, v187
	v_add_f32_e32 v223, v222, v223
	v_add_f32_e32 v222, v206, v188
	v_add_f32_e32 v223, v222, v223
	v_add_f32_e32 v222, v207, v189
	v_add_f32_e32 v223, v222, v223
	v_add_f32_e32 v222, v208, v190
	v_add_f32_e32 v223, v222, v223
	v_add_u32_e32 v214, v213, v172
	v_cvt_pk_bf16_f32 v143, v185, v186
	v_cvt_pk_bf16_f32 v144, v205, v206
	v_cvt_pk_bf16_f32 v145, v207, v208
	v_cvt_pk_bf16_f32 v146, v209, v210
	v_cvt_pk_bf16_f32 v147, v211, v212
	v_cvt_pk_bf16_f32 v136, v187, v188
	s_waitcnt lgkmcnt(2)
	v_mfma_f32_32x32x16_bf16 v[96:111], v[218:221], v[116:119], v[96:111]
	v_add_f32_e32 v222, v209, v191
	v_add_f32_e32 v223, v222, v223
	v_add_f32_e32 v222, v210, v194
	v_add_f32_e32 v223, v222, v223
	v_add_f32_e32 v222, v211, v195
	v_add_f32_e32 v223, v222, v223
	v_add_f32_e32 v222, v212, v196
	v_add_f32_e32 v223, v222, v223
	v_add_f32_e32 v168, v168, v223
	s_add_i32 s9, s71, 0x4000
	s_and_b32 s9, s9, 0x4000
	v_add_u32_e32 v222, s9, v177
	v_add_u32_e32 v197, v222, v176
	v_add_u32_e32 v202, v222, v175
	v_add_u32_e32 v203, v222, v173
	v_add_u32_e32 v204, v222, v171
	v_add_u32_e32 v205, s9, v174
	v_add_u32_e32 v206, v205, v176
	v_add_u32_e32 v207, v205, v175
	v_add_u32_e32 v208, v205, v173
	v_add_u32_e32 v205, v205, v171
	v_cvt_pk_bf16_f32 v137, v189, v190
	v_cvt_pk_bf16_f32 v138, v191, v194
	v_cvt_pk_bf16_f32 v139, v195, v196
	s_waitcnt vmcnt(1)
	ds_write_b64 v214, v[152:153] offset:32768
	v_add_u32_e32 v152, v213, v169
	s_waitcnt vmcnt(0)
	ds_write_b64 v214, v[156:157] offset:40960
	ds_write2st64_b64 v152, v[154:155], v[158:159] offset0:64 offset1:80
	s_waitcnt lgkmcnt(4)
	v_mfma_f32_32x32x16_bf16 v[96:111], v[246:249], v[120:123], v[96:111]
	s_waitcnt lgkmcnt(3)
	v_mfma_f32_32x32x16_bf16 v[96:111], v[236:239], v[124:127], v[96:111]
	s_cbranch_vccnz .LBB0_212
	v_add_u32_e32 v152, s46, v170
	ds_write_b128 v152, v[128:131]
	ds_write_b128 v152, v[132:135] offset:8192
